# grid barrier: non-leader workgroups poll the global generation word (TOPGEN) instead of the per-XCD XGEN word
# baseline (speedup 1.0000x reference)
.LBB0_506:
	s_or_b64 exec, exec, s[6:7]
	v_cvt_f32_u32_e32 v4, v2
	s_waitcnt vmcnt(0)
	v_readfirstlane_b32 s6, v3
	v_sub_u32_e32 v3, 0, v2
	v_rcp_iflag_f32_e32 v4, v4
	v_add_u32_e32 v5, s6, v1
	v_mul_f32_e32 v4, 0x4f7ffffe, v4
	v_cvt_u32_f32_e32 v4, v4
	v_mul_lo_u32 v1, v3, v4
	v_mul_hi_u32 v1, v4, v1
	v_add_u32_e32 v1, v4, v1
	v_mul_hi_u32 v1, v5, v1
	v_mul_lo_u32 v3, v1, v2
	v_sub_u32_e32 v3, v5, v3
	v_add_u32_e32 v4, 1, v1
	v_cmp_ge_u32_e32 vcc, v3, v2
	s_nop 1
	v_cndmask_b32_e32 v1, v1, v4, vcc
	v_sub_u32_e32 v4, v3, v2
	v_cndmask_b32_e32 v3, v3, v4, vcc
	v_add_u32_e32 v4, 1, v1
	v_cmp_ge_u32_e32 vcc, v3, v2
	v_add_u32_e32 v3, 1, v5
	s_nop 0
	v_cndmask_b32_e32 v1, v1, v4, vcc
	v_mul_lo_u32 v4, v2, v1
	v_add_u32_e32 v2, v4, v2
	v_cmp_ne_u32_e32 vcc, v3, v2
	s_and_saveexec_b64 s[6:7], vcc
	s_xor_b64 s[6:7], exec, s[6:7]
	s_cbranch_execz .LBB0_520
	v_readlane_b32 s8, v253, 12
	v_readlane_b32 s9, v253, 13
	s_waitcnt lgkmcnt(0)
	s_nop 3
	global_load_dword v0, v193, s[8:9] sc1
	s_waitcnt vmcnt(0)
	v_cmp_eq_u32_e32 vcc, v0, v1
	s_and_saveexec_b64 s[8:9], vcc
	s_cbranch_execz .LBB0_519
	s_mov_b32 s10, 1
	s_mov_b64 s[28:29], 0
	s_branch .LBB0_510

.LBB0_512:
	v_readlane_b32 s12, v253, 12
	v_readlane_b32 s13, v253, 13
	s_add_i32 s10, s10, 1
	s_mov_b64 s[40:41], -1
	s_nop 2
	global_load_dword v0, v193, s[12:13] sc1
	s_waitcnt vmcnt(0)
	v_cmp_ne_u32_e32 vcc, v0, v1
	s_orn2_b64 s[38:39], vcc, exec
	s_branch .LBB0_509
